# grid barrier, cross-XCC step: leaders post their arrival on TOP (no return) and poll TOP until it reaches (round+1)*#XCC instead of returning add + TOPGEN hop; no drain behind the local release
# speedup vs baseline: 1.0133x; 1.0036x over previous
.LBB0_127:
	s_andn2_saveexec_b64 s[4:5], s[4:5]
	s_cbranch_execz .LBB0_147
	s_mov_b64 s[4:5], exec
	buffer_wbl2 sc1
	s_waitcnt vmcnt(0) lgkmcnt(0)
	buffer_inv sc1
	v_add_u32_e32 v4, 1, v1
	v_mul_lo_u32 v4, v4, v0
	v_readlane_b32 s4, v254, 50
	v_readlane_b32 s5, v254, 51
	v_mov_b32_e32 v2, 0
	v_mov_b32_e32 v3, 1
	s_mov_b32 s3, 0
	s_nop 4
	global_atomic_add v2, v3, s[4:5]
.Lxb_spin_1:
	global_load_dword v3, v2, s[4:5] sc1
	s_waitcnt vmcnt(0)
	v_cmp_lt_u32_e32 vcc, v3, v4
	s_and_b64 vcc, exec, vcc
	s_cbranch_vccz .Lxb_go_1
	s_sleep 1
	s_add_i32 s3, s3, 1
	s_cmp_lt_u32 s3, 0x40000
	s_cbranch_scc1 .Lxb_spin_1
.Lxb_go_1:
	v_mov_b32_e32 v3, 1
	s_nop 0
	global_atomic_add v2, v3, s[20:21]

.LBB0_412:
	s_andn2_saveexec_b64 s[4:5], s[4:5]
	s_cbranch_execz .LBB0_432
	s_mov_b64 s[6:7], exec
	buffer_wbl2 sc1
	s_waitcnt vmcnt(0) lgkmcnt(0)
	buffer_inv sc1
	v_add_u32_e32 v4, 1, v1
	v_mul_lo_u32 v4, v4, v0
	v_readlane_b32 s6, v254, 50
	v_readlane_b32 s7, v254, 51
	v_mov_b32_e32 v2, 0
	v_mov_b32_e32 v3, 1
	s_mov_b32 s24, 0
	s_nop 4
	global_atomic_add v2, v3, s[6:7]
.Lxb_spin_2:
	global_load_dword v3, v2, s[6:7] sc1
	s_waitcnt vmcnt(0)
	v_cmp_lt_u32_e32 vcc, v3, v4
	s_and_b64 vcc, exec, vcc
	s_cbranch_vccz .Lxb_go_2
	s_sleep 1
	s_add_i32 s24, s24, 1
	s_cmp_lt_u32 s24, 0x40000
	s_cbranch_scc1 .Lxb_spin_2
.Lxb_go_2:
	v_mov_b32_e32 v3, 1
	v_readlane_b32 s6, v255, 0
	v_readlane_b32 s7, v255, 1
	s_nop 4
	global_atomic_add v2, v3, s[6:7]

.LBB0_559:
	s_andn2_saveexec_b64 s[4:5], s[4:5]
	s_cbranch_execz .LBB0_579
	s_mov_b64 s[6:7], exec
	buffer_wbl2 sc1
	s_waitcnt vmcnt(0) lgkmcnt(0)
	buffer_inv sc1
	v_add_u32_e32 v4, 1, v1
	v_mul_lo_u32 v4, v4, v0
	v_readlane_b32 s6, v254, 50
	v_readlane_b32 s7, v254, 51
	v_mov_b32_e32 v2, 0
	v_mov_b32_e32 v3, 1
	s_mov_b32 s30, 0
	s_nop 4
	global_atomic_add v2, v3, s[6:7]
.Lxb_spin_3:
	global_load_dword v3, v2, s[6:7] sc1
	s_waitcnt vmcnt(0)
	v_cmp_lt_u32_e32 vcc, v3, v4
	s_and_b64 vcc, exec, vcc
	s_cbranch_vccz .Lxb_go_3
	s_sleep 1
	s_add_i32 s30, s30, 1
	s_cmp_lt_u32 s30, 0x40000
	s_cbranch_scc1 .Lxb_spin_3

.LBB0_652:
	s_andn2_saveexec_b64 s[4:5], s[4:5]
	s_cbranch_execz .LBB0_672
	s_mov_b64 s[6:7], exec
	buffer_wbl2 sc1
	s_waitcnt vmcnt(0) lgkmcnt(0)
	buffer_inv sc1
	v_add_u32_e32 v4, 1, v1
	v_mul_lo_u32 v4, v4, v0
	v_readlane_b32 s6, v254, 50
	v_readlane_b32 s7, v254, 51
	v_mov_b32_e32 v2, 0
	v_mov_b32_e32 v3, 1
	s_mov_b32 s2, 0
	s_nop 4
	global_atomic_add v2, v3, s[6:7]
.Lxb_spin_4:
	global_load_dword v3, v2, s[6:7] sc1
	s_waitcnt vmcnt(0)
	v_cmp_lt_u32_e32 vcc, v3, v4
	s_and_b64 vcc, exec, vcc
	s_cbranch_vccz .Lxb_go_4
	s_sleep 1
	s_add_i32 s2, s2, 1
	s_cmp_lt_u32 s2, 0x40000
	s_cbranch_scc1 .Lxb_spin_4

.LBB0_725:
	s_andn2_saveexec_b64 s[6:7], s[6:7]
	s_cbranch_execz .LBB0_745
	s_mov_b64 s[10:11], exec
	buffer_wbl2 sc1
	s_waitcnt vmcnt(0) lgkmcnt(0)
	buffer_inv sc1
	v_add_u32_e32 v4, 1, v1
	v_mul_lo_u32 v4, v4, v0
	v_readlane_b32 s10, v254, 50
	v_readlane_b32 s11, v254, 51
	v_mov_b32_e32 v2, 0
	v_mov_b32_e32 v3, 1
	s_mov_b32 s2, 0
	s_nop 4
	global_atomic_add v2, v3, s[10:11]
.Lxb_spin_5:
	global_load_dword v3, v2, s[10:11] sc1
	s_waitcnt vmcnt(0)
	v_cmp_lt_u32_e32 vcc, v3, v4
	s_and_b64 vcc, exec, vcc
	s_cbranch_vccz .Lxb_go_5
	s_sleep 1
	s_add_i32 s2, s2, 1
	s_cmp_lt_u32 s2, 0x40000
	s_cbranch_scc1 .Lxb_spin_5
.Lxb_go_5:
	v_mov_b32_e32 v3, 1
	s_nop 0
	global_atomic_add v2, v3, s[34:35]

.LBB0_900:
	s_andn2_saveexec_b64 s[4:5], s[4:5]
	s_cbranch_execz .LBB0_920
	s_mov_b64 s[4:5], exec
	buffer_wbl2 sc1
	s_waitcnt vmcnt(0) lgkmcnt(0)
	buffer_inv sc1
	v_add_u32_e32 v4, 1, v1
	v_mul_lo_u32 v4, v4, v0
	v_readlane_b32 s4, v254, 50
	v_readlane_b32 s5, v254, 51
	v_mov_b32_e32 v2, 0
	v_mov_b32_e32 v3, 1
	s_mov_b32 s2, 0
	s_nop 4
	global_atomic_add v2, v3, s[4:5]
.Lxb_spin_7:
	global_load_dword v3, v2, s[4:5] sc1
	s_waitcnt vmcnt(0)
	v_cmp_lt_u32_e32 vcc, v3, v4
	s_and_b64 vcc, exec, vcc
	s_cbranch_vccz .Lxb_go_7
	s_sleep 1
	s_add_i32 s2, s2, 1
	s_cmp_lt_u32 s2, 0x40000
	s_cbranch_scc1 .Lxb_spin_7
